# x15 + the four GEMM k-loop heads aligned to 64 bytes (code placement)
# speedup vs baseline: 1.0334x; 1.0042x over previous
.LBB0_24:
	s_cmp_eq_u32 s51, 0
	s_cselect_b64 s[24:25], -1, 0
	s_and_b64 s[54:55], s[24:25], exec
	s_cselect_b32 s13, 8, 12
	s_add_i32 s54, s13, -2
	s_add_u32 s22, s22, 0x80
	s_addc_u32 s23, s23, 0
	s_add_u32 s55, s26, 0x100
	s_mov_b32 s28, 0
	s_addc_u32 s72, s27, 0
	.p2alignl 6, 3212836864

.LBB0_169:
	s_ashr_i32 s13, s12, 31
	s_lshl_b64 s[20:21], s[12:13], 20
	s_add_u32 s20, s80, s20
	s_addc_u32 s21, s81, s21
	s_and_b64 s[22:23], s[16:17], exec
	s_cselect_b32 s13, s21, s25
	s_cselect_b32 s47, s20, s24
	s_ashr_i32 s15, s14, 31
	s_lshl_b64 s[22:23], s[14:15], 20
	s_add_u32 s22, s0, s22
	s_addc_u32 s23, s1, s23
	s_and_b64 s[28:29], s[16:17], exec
	s_cselect_b32 s15, s23, s27
	s_cselect_b32 s48, s22, s26
	s_add_u32 s24, s24, 0x80080
	s_addc_u32 s25, s25, 0
	s_add_u32 s49, s26, 0x100
	v_mov_b32_e32 v0, 0
	s_addc_u32 s50, s27, 0
	s_mov_b32 s51, -2
	v_mov_b32_e32 v1, v0
	v_mov_b32_e32 v2, v0
	v_mov_b32_e32 v3, v0
	v_mov_b32_e32 v8, v0
	v_mov_b32_e32 v9, v0
	v_mov_b32_e32 v10, v0
	v_mov_b32_e32 v11, v0
	v_mov_b32_e32 v16, v0
	v_mov_b32_e32 v17, v0
	v_mov_b32_e32 v18, v0
	v_mov_b32_e32 v19, v0
	v_mov_b32_e32 v24, v0
	v_mov_b32_e32 v25, v0
	v_mov_b32_e32 v26, v0
	v_mov_b32_e32 v27, v0
	v_mov_b32_e32 v32, v0
	v_mov_b32_e32 v33, v0
	v_mov_b32_e32 v34, v0
	v_mov_b32_e32 v35, v0
	v_mov_b32_e32 v40, v0
	v_mov_b32_e32 v41, v0
	v_mov_b32_e32 v42, v0
	v_mov_b32_e32 v43, v0
	v_mov_b32_e32 v48, v0
	v_mov_b32_e32 v49, v0
	v_mov_b32_e32 v50, v0
	v_mov_b32_e32 v51, v0
	v_mov_b32_e32 v56, v0
	v_mov_b32_e32 v57, v0
	v_mov_b32_e32 v58, v0
	v_mov_b32_e32 v59, v0
	v_mov_b32_e32 v4, v0
	v_mov_b32_e32 v5, v0
	v_mov_b32_e32 v6, v0
	v_mov_b32_e32 v7, v0
	v_mov_b32_e32 v12, v0
	v_mov_b32_e32 v13, v0
	v_mov_b32_e32 v14, v0
	v_mov_b32_e32 v15, v0
	v_mov_b32_e32 v20, v0
	v_mov_b32_e32 v21, v0
	v_mov_b32_e32 v22, v0
	v_mov_b32_e32 v23, v0
	v_mov_b32_e32 v28, v0
	v_mov_b32_e32 v29, v0
	v_mov_b32_e32 v30, v0
	v_mov_b32_e32 v31, v0
	v_mov_b32_e32 v36, v0
	v_mov_b32_e32 v37, v0
	v_mov_b32_e32 v38, v0
	v_mov_b32_e32 v39, v0
	v_mov_b32_e32 v44, v0
	v_mov_b32_e32 v45, v0
	v_mov_b32_e32 v46, v0
	v_mov_b32_e32 v47, v0
	v_mov_b32_e32 v52, v0
	v_mov_b32_e32 v53, v0
	v_mov_b32_e32 v54, v0
	v_mov_b32_e32 v55, v0
	v_mov_b32_e32 v60, v0
	v_mov_b32_e32 v61, v0
	v_mov_b32_e32 v62, v0
	v_mov_b32_e32 v63, v0
	v_mov_b32_e32 v66, v0
	v_mov_b32_e32 v67, v0
	v_mov_b32_e32 v68, v0
	v_mov_b32_e32 v69, v0
	v_mov_b32_e32 v74, v0
	v_mov_b32_e32 v75, v0
	v_mov_b32_e32 v76, v0
	v_mov_b32_e32 v77, v0
	v_mov_b32_e32 v82, v0
	v_mov_b32_e32 v83, v0
	v_mov_b32_e32 v84, v0
	v_mov_b32_e32 v85, v0
	v_mov_b32_e32 v90, v0
	v_mov_b32_e32 v91, v0
	v_mov_b32_e32 v92, v0
	v_mov_b32_e32 v93, v0
	v_mov_b32_e32 v98, v0
	v_mov_b32_e32 v99, v0
	v_mov_b32_e32 v100, v0
	v_mov_b32_e32 v101, v0
	v_mov_b32_e32 v106, v0
	v_mov_b32_e32 v107, v0
	v_mov_b32_e32 v108, v0
	v_mov_b32_e32 v109, v0
	v_mov_b32_e32 v114, v0
	v_mov_b32_e32 v115, v0
	v_mov_b32_e32 v116, v0
	v_mov_b32_e32 v117, v0
	v_mov_b32_e32 v118, v0
	v_mov_b32_e32 v119, v0
	v_mov_b32_e32 v120, v0
	v_mov_b32_e32 v121, v0
	v_mov_b32_e32 v70, v0
	v_mov_b32_e32 v71, v0
	v_mov_b32_e32 v72, v0
	v_mov_b32_e32 v73, v0
	v_mov_b32_e32 v78, v0
	v_mov_b32_e32 v79, v0
	v_mov_b32_e32 v80, v0
	v_mov_b32_e32 v81, v0
	v_mov_b32_e32 v86, v0
	v_mov_b32_e32 v87, v0
	v_mov_b32_e32 v88, v0
	v_mov_b32_e32 v89, v0
	v_mov_b32_e32 v94, v0
	v_mov_b32_e32 v95, v0
	v_mov_b32_e32 v96, v0
	v_mov_b32_e32 v97, v0
	v_mov_b32_e32 v102, v0
	v_mov_b32_e32 v103, v0
	v_mov_b32_e32 v104, v0
	v_mov_b32_e32 v105, v0
	v_mov_b32_e32 v110, v0
	v_mov_b32_e32 v111, v0
	v_mov_b32_e32 v112, v0
	v_mov_b32_e32 v113, v0
	v_mov_b32_e32 v122, v0
	v_mov_b32_e32 v123, v0
	v_mov_b32_e32 v124, v0
	v_mov_b32_e32 v125, v0
	v_mov_b32_e32 v126, v0
	v_mov_b32_e32 v127, v0
	v_mov_b32_e32 v128, v0
	v_mov_b32_e32 v129, v0
	.p2alignl 6, 3212836864

.LBB0_200:
	s_add_u32 s10, s10, 0x80
	s_addc_u32 s11, s11, 0
	s_add_u32 s14, s12, 0x100
	v_mov_b32_e32 v0, 0
	s_addc_u32 s15, s13, 0
	s_mov_b32 s12, 0
	s_waitcnt lgkmcnt(0)
	v_mov_b32_e32 v1, v0
	v_mov_b32_e32 v2, v0
	v_mov_b32_e32 v3, v0
	v_mov_b32_e32 v4, v0
	v_mov_b32_e32 v5, v0
	v_mov_b32_e32 v6, v0
	v_mov_b32_e32 v7, v0
	v_mov_b32_e32 v16, v0
	v_mov_b32_e32 v17, v0
	v_mov_b32_e32 v18, v0
	v_mov_b32_e32 v19, v0
	v_mov_b32_e32 v20, v0
	v_mov_b32_e32 v21, v0
	v_mov_b32_e32 v22, v0
	v_mov_b32_e32 v23, v0
	v_mov_b32_e32 v32, v0
	v_mov_b32_e32 v33, v0
	v_mov_b32_e32 v34, v0
	v_mov_b32_e32 v35, v0
	v_mov_b32_e32 v36, v0
	v_mov_b32_e32 v37, v0
	v_mov_b32_e32 v38, v0
	v_mov_b32_e32 v39, v0
	v_mov_b32_e32 v48, v0
	v_mov_b32_e32 v49, v0
	v_mov_b32_e32 v50, v0
	v_mov_b32_e32 v51, v0
	v_mov_b32_e32 v52, v0
	v_mov_b32_e32 v53, v0
	v_mov_b32_e32 v54, v0
	v_mov_b32_e32 v55, v0
	v_mov_b32_e32 v8, v0
	v_mov_b32_e32 v9, v0
	v_mov_b32_e32 v10, v0
	v_mov_b32_e32 v11, v0
	v_mov_b32_e32 v12, v0
	v_mov_b32_e32 v13, v0
	v_mov_b32_e32 v14, v0
	v_mov_b32_e32 v15, v0
	v_mov_b32_e32 v24, v0
	v_mov_b32_e32 v25, v0
	v_mov_b32_e32 v26, v0
	v_mov_b32_e32 v27, v0
	v_mov_b32_e32 v28, v0
	v_mov_b32_e32 v29, v0
	v_mov_b32_e32 v30, v0
	v_mov_b32_e32 v31, v0
	v_mov_b32_e32 v40, v0
	v_mov_b32_e32 v41, v0
	v_mov_b32_e32 v42, v0
	v_mov_b32_e32 v43, v0
	v_mov_b32_e32 v44, v0
	v_mov_b32_e32 v45, v0
	v_mov_b32_e32 v46, v0
	v_mov_b32_e32 v47, v0
	v_mov_b32_e32 v56, v0
	v_mov_b32_e32 v57, v0
	v_mov_b32_e32 v58, v0
	v_mov_b32_e32 v59, v0
	v_mov_b32_e32 v60, v0
	v_mov_b32_e32 v61, v0
	v_mov_b32_e32 v62, v0
	v_mov_b32_e32 v63, v0
	v_mov_b32_e32 v66, v0
	v_mov_b32_e32 v67, v0
	v_mov_b32_e32 v68, v0
	v_mov_b32_e32 v69, v0
	v_mov_b32_e32 v70, v0
	v_mov_b32_e32 v71, v0
	v_mov_b32_e32 v72, v0
	v_mov_b32_e32 v73, v0
	v_mov_b32_e32 v82, v0
	v_mov_b32_e32 v83, v0
	v_mov_b32_e32 v84, v0
	v_mov_b32_e32 v85, v0
	v_mov_b32_e32 v86, v0
	v_mov_b32_e32 v87, v0
	v_mov_b32_e32 v88, v0
	v_mov_b32_e32 v89, v0
	v_mov_b32_e32 v98, v0
	v_mov_b32_e32 v99, v0
	v_mov_b32_e32 v100, v0
	v_mov_b32_e32 v101, v0
	v_mov_b32_e32 v102, v0
	v_mov_b32_e32 v103, v0
	v_mov_b32_e32 v104, v0
	v_mov_b32_e32 v105, v0
	s_waitcnt vmcnt(0)
	v_mov_b32_e32 v114, v0
	v_mov_b32_e32 v115, v0
	v_mov_b32_e32 v116, v0
	v_mov_b32_e32 v117, v0
	v_mov_b32_e32 v118, v0
	v_mov_b32_e32 v119, v0
	v_mov_b32_e32 v120, v0
	v_mov_b32_e32 v121, v0
	v_mov_b32_e32 v74, v0
	v_mov_b32_e32 v75, v0
	v_mov_b32_e32 v76, v0
	v_mov_b32_e32 v77, v0
	v_mov_b32_e32 v78, v0
	v_mov_b32_e32 v79, v0
	v_mov_b32_e32 v80, v0
	v_mov_b32_e32 v81, v0
	v_mov_b32_e32 v90, v0
	v_mov_b32_e32 v91, v0
	v_mov_b32_e32 v92, v0
	v_mov_b32_e32 v93, v0
	v_mov_b32_e32 v94, v0
	v_mov_b32_e32 v95, v0
	v_mov_b32_e32 v96, v0
	v_mov_b32_e32 v97, v0
	v_mov_b32_e32 v106, v0
	v_mov_b32_e32 v107, v0
	v_mov_b32_e32 v108, v0
	v_mov_b32_e32 v109, v0
	v_mov_b32_e32 v110, v0
	v_mov_b32_e32 v111, v0
	v_mov_b32_e32 v112, v0
	v_mov_b32_e32 v113, v0
	v_mov_b32_e32 v122, v0
	v_mov_b32_e32 v123, v0
	v_mov_b32_e32 v124, v0
	v_mov_b32_e32 v125, v0
	v_mov_b32_e32 v126, v0
	v_mov_b32_e32 v127, v0
	v_mov_b32_e32 v128, v0
	v_mov_b32_e32 v129, v0
	.p2alignl 6, 3212836864

.LBB0_322:
	s_ashr_i32 s1, s0, 31
	s_lshl_b64 s[24:25], s[0:1], 20
	s_add_u32 s24, s80, s24
	s_addc_u32 s25, s81, s25
	s_and_b64 s[26:27], s[22:23], exec
	s_cselect_b32 s1, s25, s11
	s_cselect_b32 s34, s24, s10
	s_ashr_i32 s21, s20, 31
	s_lshl_b64 s[26:27], s[20:21], 20
	s_add_u32 s26, s2, s26
	s_addc_u32 s27, s5, s27
	s_and_b64 s[30:31], s[22:23], exec
	s_cselect_b32 s21, s27, s29
	s_cselect_b32 s35, s26, s28
	s_add_u32 s10, s10, 0x80080
	s_addc_u32 s11, s11, 0
	s_add_u32 s72, s28, 0x100
	v_mov_b32_e32 v0, 0
	s_addc_u32 s73, s29, 0
	s_mov_b32 s74, -2
	s_waitcnt lgkmcnt(0)
	v_mov_b32_e32 v1, v0
	v_mov_b32_e32 v2, v0
	v_mov_b32_e32 v3, v0
	v_mov_b32_e32 v4, v0
	v_mov_b32_e32 v5, v0
	v_mov_b32_e32 v6, v0
	v_mov_b32_e32 v7, v0
	v_mov_b32_e32 v16, v0
	v_mov_b32_e32 v17, v0
	v_mov_b32_e32 v18, v0
	v_mov_b32_e32 v19, v0
	v_mov_b32_e32 v20, v0
	v_mov_b32_e32 v21, v0
	v_mov_b32_e32 v22, v0
	v_mov_b32_e32 v23, v0
	v_mov_b32_e32 v32, v0
	v_mov_b32_e32 v33, v0
	v_mov_b32_e32 v34, v0
	v_mov_b32_e32 v35, v0
	v_mov_b32_e32 v36, v0
	v_mov_b32_e32 v37, v0
	v_mov_b32_e32 v38, v0
	v_mov_b32_e32 v39, v0
	v_mov_b32_e32 v48, v0
	v_mov_b32_e32 v49, v0
	v_mov_b32_e32 v50, v0
	v_mov_b32_e32 v51, v0
	v_mov_b32_e32 v52, v0
	v_mov_b32_e32 v53, v0
	v_mov_b32_e32 v54, v0
	v_mov_b32_e32 v55, v0
	v_mov_b32_e32 v8, v0
	v_mov_b32_e32 v9, v0
	v_mov_b32_e32 v10, v0
	v_mov_b32_e32 v11, v0
	v_mov_b32_e32 v12, v0
	v_mov_b32_e32 v13, v0
	v_mov_b32_e32 v14, v0
	v_mov_b32_e32 v15, v0
	v_mov_b32_e32 v24, v0
	v_mov_b32_e32 v25, v0
	v_mov_b32_e32 v26, v0
	v_mov_b32_e32 v27, v0
	v_mov_b32_e32 v28, v0
	v_mov_b32_e32 v29, v0
	v_mov_b32_e32 v30, v0
	v_mov_b32_e32 v31, v0
	v_mov_b32_e32 v40, v0
	v_mov_b32_e32 v41, v0
	v_mov_b32_e32 v42, v0
	v_mov_b32_e32 v43, v0
	v_mov_b32_e32 v44, v0
	v_mov_b32_e32 v45, v0
	v_mov_b32_e32 v46, v0
	v_mov_b32_e32 v47, v0
	v_mov_b32_e32 v56, v0
	v_mov_b32_e32 v57, v0
	v_mov_b32_e32 v58, v0
	v_mov_b32_e32 v59, v0
	v_mov_b32_e32 v60, v0
	v_mov_b32_e32 v61, v0
	v_mov_b32_e32 v62, v0
	v_mov_b32_e32 v63, v0
	v_mov_b32_e32 v66, v0
	v_mov_b32_e32 v67, v0
	v_mov_b32_e32 v68, v0
	v_mov_b32_e32 v69, v0
	v_mov_b32_e32 v70, v0
	v_mov_b32_e32 v71, v0
	v_mov_b32_e32 v72, v0
	v_mov_b32_e32 v73, v0
	v_mov_b32_e32 v82, v0
	v_mov_b32_e32 v83, v0
	v_mov_b32_e32 v84, v0
	v_mov_b32_e32 v85, v0
	v_mov_b32_e32 v86, v0
	v_mov_b32_e32 v87, v0
	v_mov_b32_e32 v88, v0
	v_mov_b32_e32 v89, v0
	v_mov_b32_e32 v98, v0
	v_mov_b32_e32 v99, v0
	v_mov_b32_e32 v100, v0
	v_mov_b32_e32 v101, v0
	v_mov_b32_e32 v102, v0
	v_mov_b32_e32 v103, v0
	v_mov_b32_e32 v104, v0
	v_mov_b32_e32 v105, v0
	s_waitcnt vmcnt(0)
	v_mov_b32_e32 v114, v0
	v_mov_b32_e32 v115, v0
	v_mov_b32_e32 v116, v0
	v_mov_b32_e32 v117, v0
	v_mov_b32_e32 v118, v0
	v_mov_b32_e32 v119, v0
	v_mov_b32_e32 v120, v0
	v_mov_b32_e32 v121, v0
	v_mov_b32_e32 v74, v0
	v_mov_b32_e32 v75, v0
	v_mov_b32_e32 v76, v0
	v_mov_b32_e32 v77, v0
	v_mov_b32_e32 v78, v0
	v_mov_b32_e32 v79, v0
	v_mov_b32_e32 v80, v0
	v_mov_b32_e32 v81, v0
	v_mov_b32_e32 v90, v0
	v_mov_b32_e32 v91, v0
	v_mov_b32_e32 v92, v0
	v_mov_b32_e32 v93, v0
	v_mov_b32_e32 v94, v0
	v_mov_b32_e32 v95, v0
	v_mov_b32_e32 v96, v0
	v_mov_b32_e32 v97, v0
	v_mov_b32_e32 v106, v0
	v_mov_b32_e32 v107, v0
	v_mov_b32_e32 v108, v0
	v_mov_b32_e32 v109, v0
	v_mov_b32_e32 v110, v0
	v_mov_b32_e32 v111, v0
	v_mov_b32_e32 v112, v0
	v_mov_b32_e32 v113, v0
	v_mov_b32_e32 v122, v0
	v_mov_b32_e32 v123, v0
	v_mov_b32_e32 v124, v0
	v_mov_b32_e32 v125, v0
	v_mov_b32_e32 v126, v0
	v_mov_b32_e32 v127, v0
	v_mov_b32_e32 v128, v0
	v_mov_b32_e32 v129, v0
	.p2alignl 6, 3212836864
